# mix1 unit schedule rebalanced: after the first round the two half-grids swap unit slots (heavy neighbourhood-attention blocks take the pool units, light blocks the extra SSD unit); on top of final can
# speedup vs baseline: 1.0059x; 1.0059x over previous
.LBB0_130:
	s_cmpk_gt_u32 s25, 0x1ff
	s_cbranch_scc1 .Lmix1_norebal
	v_readlane_b32 s4, v253, 50
	s_nop 0
	s_cmpk_lg_u32 s4, 0x200
	s_cbranch_scc1 .Lmix1_norebal
	s_cmpk_lt_u32 s25, 0x100
	s_movk_i32 s0, 0x100
	s_cselect_b32 s0, s0, 0xffffff00
	s_add_i32 s25, s25, s0
	v_readlane_b32 s4, v255, 58
	s_lshl_b32 s5, s0, 4
	s_add_i32 s4, s4, s5
	s_nop 0
	v_writelane_b32 v255, s4, 58
	s_nop 0
	v_readlane_b32 s4, v255, 57
	s_lshl_b32 s5, s0, 6
	s_add_i32 s4, s4, s5
	s_nop 0
	v_writelane_b32 v255, s4, 57
	s_nop 0
	v_readlane_b32 s4, v255, 56
	s_add_i32 s4, s4, s0
	s_nop 0
	v_writelane_b32 v255, s4, 56
	s_nop 0
	v_readlane_b32 s4, v255, 55
	s_add_i32 s4, s4, s0
	s_nop 0
	v_writelane_b32 v255, s4, 55
	s_nop 0
